# grid barrier: non-leader workgroups poll the cross-XCD release word directly instead of the per-XCD relay word (one hop less per global barrier)
# speedup vs baseline: 1.0025x; 1.0025x over previous
; __device__ __forceinline__ unsigned xb_ld(unsigned* p)              { return __hip_atomic_load(p, __ATOMIC_RELAXED, __HIP_MEMORY_SCOPE_AGENT); }
; __device__ __forceinline__ unsigned xb_add(unsigned* p, unsigned v) { return __hip_atomic_fetch_add(p, v, __ATOMIC_RELAXED, __HIP_MEMORY_SCOPE_AGENT); }
; #define XB_SPIN(cond, bar) do { unsigned _sp = 0; while (cond) { __builtin_amdgcn_s_sleep(1); \
;     if ((++_sp & 255u) == 0u) { if (xb_ld(&(bar)[XB_TMO])) break; if (_sp > XB_SPIN_CAP) { atomicAdd(&(bar)[XB_TMO], 1u); break; } } } } while (0)
; __device__ __forceinline__ void xcd_barrier(const XcdBarrier& b) {
;     ...
;         const unsigned old = xb_add(&bar[XB_XSUB(b.x)], 1u);
;         const unsigned gen = old / nloc;
;         if (old + 1u == (gen + 1u) * nloc) {
;             __builtin_amdgcn_fence(__ATOMIC_RELEASE, "agent");
;             asm volatile("s_waitcnt vmcnt(0)" ::: "memory");
;             const unsigned og = xb_add(&bar[XB_TOP], 1u);
;             const unsigned tg = og / nx;
;             if (og + 1u == (tg + 1u) * nx) xb_add(&bar[XB_TOPGEN], 1u);
;             else XB_SPIN(xb_ld(&bar[XB_TOPGEN]) == tg, bar);
;             __builtin_amdgcn_fence(__ATOMIC_ACQUIRE, "agent");
;             xb_add(&bar[XB_XGEN(b.x)], 1u);
;             asm volatile("s_waitcnt vmcnt(0)" ::: "memory");
;         } else {
;             XB_SPIN(xb_ld(&bar[XB_XGEN(b.x)]) == gen, bar);
;             __builtin_amdgcn_fence(__ATOMIC_ACQUIRE, "agent");
;             asm volatile("s_waitcnt vmcnt(0)" ::: "memory");
;         }
.LBB0_225:
	s_or_b64 exec, exec, s[14:15]
	v_cvt_f32_u32_e32 v4, v2
	s_waitcnt vmcnt(0)
	v_readfirstlane_b32 s2, v3
	v_sub_u32_e32 v3, 0, v2
	v_rcp_iflag_f32_e32 v4, v4
	v_add_u32_e32 v5, s2, v1
	v_mul_f32_e32 v4, 0x4f7ffffe, v4
	v_cvt_u32_f32_e32 v4, v4
	v_mul_lo_u32 v1, v3, v4
	v_mul_hi_u32 v1, v4, v1
	v_add_u32_e32 v1, v4, v1
	v_mul_hi_u32 v1, v5, v1
	v_mul_lo_u32 v3, v1, v2
	v_sub_u32_e32 v3, v5, v3
	v_add_u32_e32 v4, 1, v1
	v_sub_u32_e32 v6, v3, v2
	v_cmp_ge_u32_e32 vcc, v3, v2
	s_nop 1
	v_cndmask_b32_e32 v1, v1, v4, vcc
	v_cndmask_b32_e32 v3, v3, v6, vcc
	v_add_u32_e32 v4, 1, v1
	v_cmp_ge_u32_e32 vcc, v3, v2
	v_add_u32_e32 v3, 1, v5
	s_nop 0
	v_cndmask_b32_e32 v1, v1, v4, vcc
	v_mul_lo_u32 v4, v2, v1
	v_add_u32_e32 v2, v4, v2
	v_cmp_ne_u32_e32 vcc, v3, v2
	s_and_saveexec_b64 s[12:13], vcc
	s_xor_b64 s[12:13], exec, s[12:13]
	s_cbranch_execz .LBB0_239
	s_waitcnt lgkmcnt(0)
	s_add_u32 s18, s6, 0x9783500
	s_addc_u32 s19, s7, 0
	global_load_dword v0, v65, s[18:19] sc1
	s_waitcnt vmcnt(0)
	v_cmp_eq_u32_e32 vcc, v0, v1
	s_and_saveexec_b64 s[14:15], vcc
	s_cbranch_execz .LBB0_238
	s_add_u32 s16, s6, 0x9780200
	s_addc_u32 s17, s7, 0
	s_mov_b32 s2, 1
	s_mov_b64 s[20:21], 0
	s_branch .LBB0_229

; __device__ __forceinline__ unsigned xb_ld(unsigned* p)              { return __hip_atomic_load(p, __ATOMIC_RELAXED, __HIP_MEMORY_SCOPE_AGENT); }
; __device__ __forceinline__ unsigned xb_add(unsigned* p, unsigned v) { return __hip_atomic_fetch_add(p, v, __ATOMIC_RELAXED, __HIP_MEMORY_SCOPE_AGENT); }
; #define XB_SPIN(cond, bar) do { unsigned _sp = 0; while (cond) { __builtin_amdgcn_s_sleep(1); \
;     if ((++_sp & 255u) == 0u) { if (xb_ld(&(bar)[XB_TMO])) break; if (_sp > XB_SPIN_CAP) { atomicAdd(&(bar)[XB_TMO], 1u); break; } } } } while (0)
; __device__ __forceinline__ void xcd_barrier(const XcdBarrier& b) {
;     ...
;         const unsigned old = xb_add(&bar[XB_XSUB(b.x)], 1u);
;         const unsigned gen = old / nloc;
;         if (old + 1u == (gen + 1u) * nloc) {
;             __builtin_amdgcn_fence(__ATOMIC_RELEASE, "agent");
;             asm volatile("s_waitcnt vmcnt(0)" ::: "memory");
;             const unsigned og = xb_add(&bar[XB_TOP], 1u);
;             const unsigned tg = og / nx;
;             if (og + 1u == (tg + 1u) * nx) xb_add(&bar[XB_TOPGEN], 1u);
;             else XB_SPIN(xb_ld(&bar[XB_TOPGEN]) == tg, bar);
;             __builtin_amdgcn_fence(__ATOMIC_ACQUIRE, "agent");
;             xb_add(&bar[XB_XGEN(b.x)], 1u);
;             asm volatile("s_waitcnt vmcnt(0)" ::: "memory");
;         } else {
;             XB_SPIN(xb_ld(&bar[XB_XGEN(b.x)]) == gen, bar);
;             __builtin_amdgcn_fence(__ATOMIC_ACQUIRE, "agent");
;             asm volatile("s_waitcnt vmcnt(0)" ::: "memory");
;         }
.LBB0_352:
	s_or_b64 exec, exec, s[12:13]
	v_cvt_f32_u32_e32 v4, v2
	s_waitcnt vmcnt(0)
	v_readfirstlane_b32 s2, v3
	v_sub_u32_e32 v3, 0, v2
	v_rcp_iflag_f32_e32 v4, v4
	v_add_u32_e32 v5, s2, v1
	v_mul_f32_e32 v4, 0x4f7ffffe, v4
	v_cvt_u32_f32_e32 v4, v4
	v_mul_lo_u32 v1, v3, v4
	v_mul_hi_u32 v1, v4, v1
	v_add_u32_e32 v1, v4, v1
	v_mul_hi_u32 v1, v5, v1
	v_mul_lo_u32 v3, v1, v2
	v_sub_u32_e32 v3, v5, v3
	v_add_u32_e32 v4, 1, v1
	v_cmp_ge_u32_e32 vcc, v3, v2
	s_nop 1
	v_cndmask_b32_e32 v1, v1, v4, vcc
	v_sub_u32_e32 v4, v3, v2
	v_cndmask_b32_e32 v3, v3, v4, vcc
	v_add_u32_e32 v4, 1, v1
	v_cmp_ge_u32_e32 vcc, v3, v2
	v_add_u32_e32 v3, 1, v5
	s_nop 0
	v_cndmask_b32_e32 v1, v1, v4, vcc
	v_mul_lo_u32 v4, v2, v1
	v_add_u32_e32 v2, v4, v2
	v_cmp_ne_u32_e32 vcc, v3, v2
	s_and_saveexec_b64 s[10:11], vcc
	s_xor_b64 s[10:11], exec, s[10:11]
	s_cbranch_execz .LBB0_366
	s_waitcnt lgkmcnt(0)
	s_add_u32 s16, s6, 0x9783500
	s_addc_u32 s17, s7, 0
	global_load_dword v0, v65, s[16:17] sc1
	s_waitcnt vmcnt(0)
	v_cmp_eq_u32_e32 vcc, v0, v1
	s_and_saveexec_b64 s[12:13], vcc
	s_cbranch_execz .LBB0_365
	s_add_u32 s14, s6, 0x9780200
	s_addc_u32 s15, s7, 0
	s_mov_b32 s2, 1
	s_mov_b64 s[18:19], 0
	s_branch .LBB0_356

; __device__ __forceinline__ unsigned xb_ld(unsigned* p)              { return __hip_atomic_load(p, __ATOMIC_RELAXED, __HIP_MEMORY_SCOPE_AGENT); }
; __device__ __forceinline__ unsigned xb_add(unsigned* p, unsigned v) { return __hip_atomic_fetch_add(p, v, __ATOMIC_RELAXED, __HIP_MEMORY_SCOPE_AGENT); }
; #define XB_SPIN(cond, bar) do { unsigned _sp = 0; while (cond) { __builtin_amdgcn_s_sleep(1); \
;     if ((++_sp & 255u) == 0u) { if (xb_ld(&(bar)[XB_TMO])) break; if (_sp > XB_SPIN_CAP) { atomicAdd(&(bar)[XB_TMO], 1u); break; } } } } while (0)
; __device__ __forceinline__ void xcd_barrier(const XcdBarrier& b) {
;     ...
;         const unsigned old = xb_add(&bar[XB_XSUB(b.x)], 1u);
;         const unsigned gen = old / nloc;
;         if (old + 1u == (gen + 1u) * nloc) {
;             __builtin_amdgcn_fence(__ATOMIC_RELEASE, "agent");
;             asm volatile("s_waitcnt vmcnt(0)" ::: "memory");
;             const unsigned og = xb_add(&bar[XB_TOP], 1u);
;             const unsigned tg = og / nx;
;             if (og + 1u == (tg + 1u) * nx) xb_add(&bar[XB_TOPGEN], 1u);
;             else XB_SPIN(xb_ld(&bar[XB_TOPGEN]) == tg, bar);
;             __builtin_amdgcn_fence(__ATOMIC_ACQUIRE, "agent");
;             xb_add(&bar[XB_XGEN(b.x)], 1u);
;             asm volatile("s_waitcnt vmcnt(0)" ::: "memory");
;         } else {
;             XB_SPIN(xb_ld(&bar[XB_XGEN(b.x)]) == gen, bar);
;             __builtin_amdgcn_fence(__ATOMIC_ACQUIRE, "agent");
;             asm volatile("s_waitcnt vmcnt(0)" ::: "memory");
;         }
.LBB0_482:
	s_or_b64 exec, exec, s[14:15]
	v_cvt_f32_u32_e32 v4, v2
	s_waitcnt vmcnt(0)
	v_readfirstlane_b32 s2, v3
	v_sub_u32_e32 v3, 0, v2
	v_rcp_iflag_f32_e32 v4, v4
	v_add_u32_e32 v5, s2, v1
	v_mul_f32_e32 v4, 0x4f7ffffe, v4
	v_cvt_u32_f32_e32 v4, v4
	v_mul_lo_u32 v1, v3, v4
	v_mul_hi_u32 v1, v4, v1
	v_add_u32_e32 v1, v4, v1
	v_mul_hi_u32 v1, v5, v1
	v_mul_lo_u32 v3, v1, v2
	v_sub_u32_e32 v3, v5, v3
	v_add_u32_e32 v4, 1, v1
	v_cmp_ge_u32_e32 vcc, v3, v2
	s_nop 1
	v_cndmask_b32_e32 v1, v1, v4, vcc
	v_sub_u32_e32 v4, v3, v2
	v_cndmask_b32_e32 v3, v3, v4, vcc
	v_add_u32_e32 v4, 1, v1
	v_cmp_ge_u32_e32 vcc, v3, v2
	v_add_u32_e32 v3, 1, v5
	s_nop 0
	v_cndmask_b32_e32 v1, v1, v4, vcc
	v_mul_lo_u32 v4, v2, v1
	v_add_u32_e32 v2, v4, v2
	v_cmp_ne_u32_e32 vcc, v3, v2
	s_and_saveexec_b64 s[12:13], vcc
	s_xor_b64 s[12:13], exec, s[12:13]
	s_cbranch_execz .LBB0_496
	s_waitcnt lgkmcnt(0)
	s_add_u32 s18, s6, 0x9783500
	s_addc_u32 s19, s7, 0
	global_load_dword v0, v65, s[18:19] sc1
	s_waitcnt vmcnt(0)
	v_cmp_eq_u32_e32 vcc, v0, v1
	s_and_saveexec_b64 s[14:15], vcc
	s_cbranch_execz .LBB0_495
	s_add_u32 s16, s6, 0x9780200
	s_addc_u32 s17, s7, 0
	s_mov_b32 s2, 1
	s_mov_b64 s[20:21], 0
	s_branch .LBB0_486

; __device__ __forceinline__ unsigned xb_ld(unsigned* p)              { return __hip_atomic_load(p, __ATOMIC_RELAXED, __HIP_MEMORY_SCOPE_AGENT); }
; __device__ __forceinline__ unsigned xb_add(unsigned* p, unsigned v) { return __hip_atomic_fetch_add(p, v, __ATOMIC_RELAXED, __HIP_MEMORY_SCOPE_AGENT); }
; #define XB_SPIN(cond, bar) do { unsigned _sp = 0; while (cond) { __builtin_amdgcn_s_sleep(1); \
;     if ((++_sp & 255u) == 0u) { if (xb_ld(&(bar)[XB_TMO])) break; if (_sp > XB_SPIN_CAP) { atomicAdd(&(bar)[XB_TMO], 1u); break; } } } } while (0)
; __device__ __forceinline__ void xcd_barrier(const XcdBarrier& b) {
;     ...
;         const unsigned old = xb_add(&bar[XB_XSUB(b.x)], 1u);
;         const unsigned gen = old / nloc;
;         if (old + 1u == (gen + 1u) * nloc) {
;             __builtin_amdgcn_fence(__ATOMIC_RELEASE, "agent");
;             asm volatile("s_waitcnt vmcnt(0)" ::: "memory");
;             const unsigned og = xb_add(&bar[XB_TOP], 1u);
;             const unsigned tg = og / nx;
;             if (og + 1u == (tg + 1u) * nx) xb_add(&bar[XB_TOPGEN], 1u);
;             else XB_SPIN(xb_ld(&bar[XB_TOPGEN]) == tg, bar);
;             __builtin_amdgcn_fence(__ATOMIC_ACQUIRE, "agent");
;             xb_add(&bar[XB_XGEN(b.x)], 1u);
;             asm volatile("s_waitcnt vmcnt(0)" ::: "memory");
;         } else {
;             XB_SPIN(xb_ld(&bar[XB_XGEN(b.x)]) == gen, bar);
;             __builtin_amdgcn_fence(__ATOMIC_ACQUIRE, "agent");
;             asm volatile("s_waitcnt vmcnt(0)" ::: "memory");
;         }
.LBB0_944:
	s_or_b64 exec, exec, s[12:13]
	v_cvt_f32_u32_e32 v4, v2
	s_waitcnt vmcnt(0)
	v_readfirstlane_b32 s2, v3
	v_sub_u32_e32 v3, 0, v2
	v_rcp_iflag_f32_e32 v4, v4
	v_add_u32_e32 v5, s2, v1
	v_mul_f32_e32 v4, 0x4f7ffffe, v4
	v_cvt_u32_f32_e32 v4, v4
	v_mul_lo_u32 v1, v3, v4
	v_mul_hi_u32 v1, v4, v1
	v_add_u32_e32 v1, v4, v1
	v_mul_hi_u32 v1, v5, v1
	v_mul_lo_u32 v3, v1, v2
	v_sub_u32_e32 v3, v5, v3
	v_add_u32_e32 v4, 1, v1
	v_cmp_ge_u32_e32 vcc, v3, v2
	s_nop 1
	v_cndmask_b32_e32 v1, v1, v4, vcc
	v_sub_u32_e32 v4, v3, v2
	v_cndmask_b32_e32 v3, v3, v4, vcc
	v_add_u32_e32 v4, 1, v1
	v_cmp_ge_u32_e32 vcc, v3, v2
	v_add_u32_e32 v3, 1, v5
	s_nop 0
	v_cndmask_b32_e32 v1, v1, v4, vcc
	v_mul_lo_u32 v4, v2, v1
	v_add_u32_e32 v2, v4, v2
	v_cmp_ne_u32_e32 vcc, v3, v2
	s_and_saveexec_b64 s[10:11], vcc
	s_xor_b64 s[10:11], exec, s[10:11]
	s_cbranch_execz .LBB0_958
	s_waitcnt lgkmcnt(0)
	s_add_u32 s18, s6, 0x9783500
	s_addc_u32 s19, s7, 0
	global_load_dword v0, v65, s[18:19] sc1
	s_waitcnt vmcnt(0)
	v_cmp_eq_u32_e32 vcc, v0, v1
	s_and_saveexec_b64 s[12:13], vcc
	s_cbranch_execz .LBB0_957
	s_add_u32 s14, s6, 0x9780200
	s_addc_u32 s15, s7, 0
	s_mov_b32 s2, 1
	s_mov_b64 s[20:21], 0
	s_branch .LBB0_948

; __device__ __forceinline__ unsigned xb_ld(unsigned* p)              { return __hip_atomic_load(p, __ATOMIC_RELAXED, __HIP_MEMORY_SCOPE_AGENT); }
; __device__ __forceinline__ unsigned xb_add(unsigned* p, unsigned v) { return __hip_atomic_fetch_add(p, v, __ATOMIC_RELAXED, __HIP_MEMORY_SCOPE_AGENT); }
; #define XB_SPIN(cond, bar) do { unsigned _sp = 0; while (cond) { __builtin_amdgcn_s_sleep(1); \
;     if ((++_sp & 255u) == 0u) { if (xb_ld(&(bar)[XB_TMO])) break; if (_sp > XB_SPIN_CAP) { atomicAdd(&(bar)[XB_TMO], 1u); break; } } } } while (0)
; __device__ __forceinline__ void xcd_barrier(const XcdBarrier& b) {
;     ...
;         const unsigned old = xb_add(&bar[XB_XSUB(b.x)], 1u);
;         const unsigned gen = old / nloc;
;         if (old + 1u == (gen + 1u) * nloc) {
;             __builtin_amdgcn_fence(__ATOMIC_RELEASE, "agent");
;             asm volatile("s_waitcnt vmcnt(0)" ::: "memory");
;             const unsigned og = xb_add(&bar[XB_TOP], 1u);
;             const unsigned tg = og / nx;
;             if (og + 1u == (tg + 1u) * nx) xb_add(&bar[XB_TOPGEN], 1u);
;             else XB_SPIN(xb_ld(&bar[XB_TOPGEN]) == tg, bar);
;             __builtin_amdgcn_fence(__ATOMIC_ACQUIRE, "agent");
;             xb_add(&bar[XB_XGEN(b.x)], 1u);
;             asm volatile("s_waitcnt vmcnt(0)" ::: "memory");
;         } else {
;             XB_SPIN(xb_ld(&bar[XB_XGEN(b.x)]) == gen, bar);
;             __builtin_amdgcn_fence(__ATOMIC_ACQUIRE, "agent");
;             asm volatile("s_waitcnt vmcnt(0)" ::: "memory");
;         }
.LBB0_1000:
	s_or_b64 exec, exec, s[14:15]
	v_cvt_f32_u32_e32 v4, v2
	s_waitcnt vmcnt(0)
	v_readfirstlane_b32 s2, v3
	v_sub_u32_e32 v3, 0, v2
	v_rcp_iflag_f32_e32 v4, v4
	v_add_u32_e32 v5, s2, v1
	v_mul_f32_e32 v4, 0x4f7ffffe, v4
	v_cvt_u32_f32_e32 v4, v4
	v_mul_lo_u32 v1, v3, v4
	v_mul_hi_u32 v1, v4, v1
	v_add_u32_e32 v1, v4, v1
	v_mul_hi_u32 v1, v5, v1
	v_mul_lo_u32 v3, v1, v2
	v_sub_u32_e32 v3, v5, v3
	v_add_u32_e32 v4, 1, v1
	v_cmp_ge_u32_e32 vcc, v3, v2
	s_nop 1
	v_cndmask_b32_e32 v1, v1, v4, vcc
	v_sub_u32_e32 v4, v3, v2
	v_cndmask_b32_e32 v3, v3, v4, vcc
	v_add_u32_e32 v4, 1, v1
	v_cmp_ge_u32_e32 vcc, v3, v2
	v_add_u32_e32 v3, 1, v5
	s_nop 0
	v_cndmask_b32_e32 v1, v1, v4, vcc
	v_mul_lo_u32 v4, v2, v1
	v_add_u32_e32 v2, v4, v2
	v_cmp_ne_u32_e32 vcc, v3, v2
	s_and_saveexec_b64 s[12:13], vcc
	s_xor_b64 s[12:13], exec, s[12:13]
	s_cbranch_execz .LBB0_1014
	s_waitcnt lgkmcnt(0)
	s_add_u32 s20, s4, 0x9783500
	s_addc_u32 s21, s5, 0
	global_load_dword v0, v65, s[20:21] sc1
	s_waitcnt vmcnt(0)
	v_cmp_eq_u32_e32 vcc, v0, v1
	s_and_saveexec_b64 s[14:15], vcc
	s_cbranch_execz .LBB0_1013
	s_add_u32 s18, s4, 0x9780200
	s_addc_u32 s19, s5, 0
	s_mov_b32 s2, 1
	s_mov_b64 s[22:23], 0
	s_branch .LBB0_1004

; __device__ __forceinline__ unsigned xb_ld(unsigned* p)              { return __hip_atomic_load(p, __ATOMIC_RELAXED, __HIP_MEMORY_SCOPE_AGENT); }
; __device__ __forceinline__ unsigned xb_add(unsigned* p, unsigned v) { return __hip_atomic_fetch_add(p, v, __ATOMIC_RELAXED, __HIP_MEMORY_SCOPE_AGENT); }
; #define XB_SPIN(cond, bar) do { unsigned _sp = 0; while (cond) { __builtin_amdgcn_s_sleep(1); \
;     if ((++_sp & 255u) == 0u) { if (xb_ld(&(bar)[XB_TMO])) break; if (_sp > XB_SPIN_CAP) { atomicAdd(&(bar)[XB_TMO], 1u); break; } } } } while (0)
; __device__ __forceinline__ void xcd_barrier(const XcdBarrier& b) {
;     ...
;         const unsigned old = xb_add(&bar[XB_XSUB(b.x)], 1u);
;         const unsigned gen = old / nloc;
;         if (old + 1u == (gen + 1u) * nloc) {
;             __builtin_amdgcn_fence(__ATOMIC_RELEASE, "agent");
;             asm volatile("s_waitcnt vmcnt(0)" ::: "memory");
;             const unsigned og = xb_add(&bar[XB_TOP], 1u);
;             const unsigned tg = og / nx;
;             if (og + 1u == (tg + 1u) * nx) xb_add(&bar[XB_TOPGEN], 1u);
;             else XB_SPIN(xb_ld(&bar[XB_TOPGEN]) == tg, bar);
;             __builtin_amdgcn_fence(__ATOMIC_ACQUIRE, "agent");
;             xb_add(&bar[XB_XGEN(b.x)], 1u);
;             asm volatile("s_waitcnt vmcnt(0)" ::: "memory");
;         } else {
;             XB_SPIN(xb_ld(&bar[XB_XGEN(b.x)]) == gen, bar);
;             __builtin_amdgcn_fence(__ATOMIC_ACQUIRE, "agent");
;             asm volatile("s_waitcnt vmcnt(0)" ::: "memory");
;         }
.LBB0_1138:
	s_or_b64 exec, exec, s[10:11]
	v_cvt_f32_u32_e32 v4, v2
	s_waitcnt vmcnt(0)
	v_readfirstlane_b32 s2, v3
	v_sub_u32_e32 v3, 0, v2
	v_rcp_iflag_f32_e32 v4, v4
	v_add_u32_e32 v5, s2, v1
	v_mul_f32_e32 v4, 0x4f7ffffe, v4
	v_cvt_u32_f32_e32 v4, v4
	v_mul_lo_u32 v1, v3, v4
	v_mul_hi_u32 v1, v4, v1
	v_add_u32_e32 v1, v4, v1
	v_mul_hi_u32 v1, v5, v1
	v_mul_lo_u32 v3, v1, v2
	v_sub_u32_e32 v3, v5, v3
	v_add_u32_e32 v4, 1, v1
	v_cmp_ge_u32_e32 vcc, v3, v2
	s_nop 1
	v_cndmask_b32_e32 v1, v1, v4, vcc
	v_sub_u32_e32 v4, v3, v2
	v_cndmask_b32_e32 v3, v3, v4, vcc
	v_add_u32_e32 v4, 1, v1
	v_cmp_ge_u32_e32 vcc, v3, v2
	v_add_u32_e32 v3, 1, v5
	s_nop 0
	v_cndmask_b32_e32 v1, v1, v4, vcc
	v_mul_lo_u32 v4, v2, v1
	v_add_u32_e32 v2, v4, v2
	v_cmp_ne_u32_e32 vcc, v3, v2
	s_and_saveexec_b64 s[8:9], vcc
	s_xor_b64 s[8:9], exec, s[8:9]
	s_cbranch_execz .LBB0_1152
	s_waitcnt lgkmcnt(0)
	s_add_u32 s14, s4, 0x9783500
	s_addc_u32 s15, s5, 0
	global_load_dword v0, v65, s[14:15] sc1
	s_waitcnt vmcnt(0)
	v_cmp_eq_u32_e32 vcc, v0, v1
	s_and_saveexec_b64 s[10:11], vcc
	s_cbranch_execz .LBB0_1151
	s_add_u32 s12, s4, 0x9780200
	s_addc_u32 s13, s5, 0
	s_mov_b32 s2, 1
	s_mov_b64 s[18:19], 0
	s_branch .LBB0_1142

; __device__ __forceinline__ unsigned xb_ld(unsigned* p)              { return __hip_atomic_load(p, __ATOMIC_RELAXED, __HIP_MEMORY_SCOPE_AGENT); }
; __device__ __forceinline__ unsigned xb_add(unsigned* p, unsigned v) { return __hip_atomic_fetch_add(p, v, __ATOMIC_RELAXED, __HIP_MEMORY_SCOPE_AGENT); }
; #define XB_SPIN(cond, bar) do { unsigned _sp = 0; while (cond) { __builtin_amdgcn_s_sleep(1); \
;     if ((++_sp & 255u) == 0u) { if (xb_ld(&(bar)[XB_TMO])) break; if (_sp > XB_SPIN_CAP) { atomicAdd(&(bar)[XB_TMO], 1u); break; } } } } while (0)
; __device__ __forceinline__ void xcd_barrier(const XcdBarrier& b) {
;     ...
;         const unsigned old = xb_add(&bar[XB_XSUB(b.x)], 1u);
;         const unsigned gen = old / nloc;
;         if (old + 1u == (gen + 1u) * nloc) {
;             __builtin_amdgcn_fence(__ATOMIC_RELEASE, "agent");
;             asm volatile("s_waitcnt vmcnt(0)" ::: "memory");
;             const unsigned og = xb_add(&bar[XB_TOP], 1u);
;             const unsigned tg = og / nx;
;             if (og + 1u == (tg + 1u) * nx) xb_add(&bar[XB_TOPGEN], 1u);
;             else XB_SPIN(xb_ld(&bar[XB_TOPGEN]) == tg, bar);
;             __builtin_amdgcn_fence(__ATOMIC_ACQUIRE, "agent");
;             xb_add(&bar[XB_XGEN(b.x)], 1u);
;             asm volatile("s_waitcnt vmcnt(0)" ::: "memory");
;         } else {
;             XB_SPIN(xb_ld(&bar[XB_XGEN(b.x)]) == gen, bar);
;             __builtin_amdgcn_fence(__ATOMIC_ACQUIRE, "agent");
;             asm volatile("s_waitcnt vmcnt(0)" ::: "memory");
;         }
.LBB0_1228:
	s_or_b64 exec, exec, s[10:11]
	v_cvt_f32_u32_e32 v4, v2
	s_waitcnt vmcnt(0)
	v_readfirstlane_b32 s2, v3
	v_sub_u32_e32 v3, 0, v2
	v_rcp_iflag_f32_e32 v4, v4
	v_add_u32_e32 v5, s2, v1
	v_mul_f32_e32 v4, 0x4f7ffffe, v4
	v_cvt_u32_f32_e32 v4, v4
	v_mul_lo_u32 v1, v3, v4
	v_mul_hi_u32 v1, v4, v1
	v_add_u32_e32 v1, v4, v1
	v_mul_hi_u32 v1, v5, v1
	v_mul_lo_u32 v3, v1, v2
	v_sub_u32_e32 v3, v5, v3
	v_add_u32_e32 v4, 1, v1
	v_cmp_ge_u32_e32 vcc, v3, v2
	s_nop 1
	v_cndmask_b32_e32 v1, v1, v4, vcc
	v_sub_u32_e32 v4, v3, v2
	v_cndmask_b32_e32 v3, v3, v4, vcc
	v_add_u32_e32 v4, 1, v1
	v_cmp_ge_u32_e32 vcc, v3, v2
	v_add_u32_e32 v3, 1, v5
	s_nop 0
	v_cndmask_b32_e32 v1, v1, v4, vcc
	v_mul_lo_u32 v4, v2, v1
	v_add_u32_e32 v2, v4, v2
	v_cmp_ne_u32_e32 vcc, v3, v2
	s_and_saveexec_b64 s[8:9], vcc
	s_xor_b64 s[8:9], exec, s[8:9]
	s_cbranch_execz .LBB0_1242
	s_waitcnt lgkmcnt(0)
	s_add_u32 s14, s4, 0x9783500
	s_addc_u32 s15, s5, 0
	global_load_dword v0, v65, s[14:15] sc1
	s_waitcnt vmcnt(0)
	v_cmp_eq_u32_e32 vcc, v0, v1
	s_and_saveexec_b64 s[10:11], vcc
	s_cbranch_execz .LBB0_1241
	s_add_u32 s12, s4, 0x9780200
	s_addc_u32 s13, s5, 0
	s_mov_b32 s2, 1
	s_mov_b64 s[16:17], 0
	s_branch .LBB0_1232
